# phase_out GLA branch: hoisted all 72 global loads per direction ahead of the MFMA chain (were serialized one round trip per MFMA)
# speedup vs baseline: 1.0398x; 1.0398x over previous
.LBB0_93:
	s_mov_b64 s[4:5], 0
	v_writelane_b32 v255, s4, 1
	s_nop 1
	v_writelane_b32 v255, s5, 2
	s_cbranch_execz .LBB0_308
	v_readlane_b32 s0, v255, 0
	s_cmp_lt_i32 s0, 5
	s_mov_b64 s[0:1], -1
	s_cbranch_scc1 .LBB0_167
	v_readlane_b32 s0, v255, 0
	s_cmp_eq_u32 s0, 5
	s_cbranch_scc0 .LBB0_166
	v_mov_b32_e32 v35, v0
	s_mov_b32 s16, s2
	s_cmpk_gt_i32 s16, 0x3ff
	s_cbranch_scc1 .LBB0_166
	v_bfe_u32 v41, v35, 5, 1
	v_lshlrev_b32_e32 v12, 4, v35
	v_readlane_b32 s0, v253, 20
	v_and_b32_e32 v130, 0xf0, v12
	v_readlane_b32 s1, v253, 21
	v_lshlrev_b32_e32 v13, 2, v41
	v_bfe_u32 v5, v35, 6, 1
	v_ashrrev_i32_e32 v10, 7, v35
	v_lshl_add_u64 v[38:39], s[0:1], 0, v[130:131]
	v_add_u32_e32 v42, 0, v13
	s_movk_i32 s0, 0xfc
	v_and_b32_e32 v3, 63, v35
	v_and_b32_e32 v34, 31, v35
	v_cmp_le_i32_e64 s[50:51], v5, v10
	v_lshlrev_b32_e32 v44, 5, v5
	v_lshlrev_b32_e32 v8, 7, v5
	v_mad_u32_u24 v5, v41, s0, v42
	v_readlane_b32 s0, v253, 30
	v_lshlrev_b32_e32 v6, 2, v3
	v_add_u32_e32 v40, 0, v130
	v_lshlrev_b32_e32 v2, 2, v34
	v_cmp_eq_u32_e64 s[52:53], 0, v3
	v_cmp_gt_u32_e64 s[40:41], 2, v3
	v_cmp_gt_u32_e64 s[42:43], 4, v3
	v_cmp_gt_u32_e64 s[44:45], 8, v3
	v_cmp_gt_u32_e64 s[46:47], 16, v3
	v_cmp_gt_u32_e64 s[48:49], 32, v3
	v_lshlrev_b32_e32 v130, 8, v41
	v_mov_b32_e32 v3, v131
	v_readlane_b32 s1, v253, 31
	v_add_u32_e32 v11, 0, v6
	v_add_u32_e32 v43, s84, v6
	v_lshl_add_u64 v[6:7], s[68:69], 0, v[130:131]
	v_mov_b32_e32 v9, v131
	v_add3_u32 v67, v5, v8, v2
	v_ashrrev_i32_e32 v5, 5, v35
	v_lshl_add_u64 v[50:51], s[0:1], 0, v[2:3]
	v_readlane_b32 s0, v253, 28
	v_writelane_b32 v255, s60, 3
	v_lshl_add_u64 v[6:7], v[6:7], 0, v[8:9]
	v_lshlrev_b32_e32 v87, 3, v5
	v_readlane_b32 s1, v253, 29
	v_writelane_b32 v255, s61, 4
	v_add_u32_e32 v4, 0, v2
	v_lshl_add_u64 v[46:47], v[6:7], 0, v[2:3]
	s_movk_i32 s6, 0x84
	v_lshl_add_u64 v[6:7], s[0:1], 0, v[130:131]
	s_lshl_b32 s0, s24, 6
	v_or_b32_e32 v116, 1, v87
	s_movk_i32 s4, 0x420
	v_writelane_b32 v255, s62, 5
	v_or_b32_e32 v55, v44, v34
	s_ashr_i32 s1, s0, 31
	v_mad_u64_u32 v[62:63], s[4:5], v5, s4, v[4:5]
	v_mad_u64_u32 v[64:65], s[4:5], v116, s6, v[4:5]
	v_writelane_b32 v255, s63, 6
	v_mul_u32_u24_e32 v15, 0x84, v55
	v_lshl_add_u64 v[6:7], v[6:7], 0, v[8:9]
	s_add_i32 s4, 0, 0xc300
	s_lshl_b64 s[0:1], s[0:1], 2
	v_lshlrev_b32_e32 v45, 5, v10
	v_add_u32_e32 v89, s84, v2
	v_lshl_add_u64 v[52:53], v[6:7], 0, v[2:3]
	v_ashrrev_i32_e32 v3, 2, v35
	v_and_b32_e32 v2, 3, v35
	v_add_u32_e32 v7, 0x100, v35
	v_add_u32_e32 v9, 0x200, v35
	v_add_u32_e32 v17, 0x300, v35
	v_add_u32_e32 v19, 0x400, v35
	v_add_u32_e32 v20, 0x500, v35
	v_add_u32_e32 v21, 0x600, v35
	v_add_u32_e32 v22, 0x700, v35
	v_add_u32_e32 v23, 0x800, v35
	v_add_u32_e32 v24, 0x900, v35
	v_add_u32_e32 v25, 0xa00, v35
	v_add_u32_e32 v26, 0xb00, v35
	v_add_u32_e32 v27, 0xc00, v35
	v_add_u32_e32 v28, 0xd00, v35
	v_add_u32_e32 v29, 0xe00, v35
	v_add_u32_e32 v30, 0xf00, v35
	v_add_u32_e32 v206, s4, v13
	v_add3_u32 v207, v15, v13, s4
	s_movk_i32 s4, 0x1080
	v_writelane_b32 v255, s0, 9
	v_lshlrev_b32_e32 v36, 2, v35
	v_or_b32_e32 v49, v45, v34
	v_add_u32_e32 v48, v4, v8
	v_mul_lo_u32 v3, v3, s85
	v_lshlrev_b32_e32 v6, 6, v2
	v_lshlrev_b32_e32 v54, 4, v2
	v_ashrrev_i32_e32 v2, 6, v35
	v_ashrrev_i32_e32 v8, 6, v7
	v_ashrrev_i32_e32 v16, 6, v9
	v_ashrrev_i32_e32 v18, 6, v17
	v_ashrrev_i32_e32 v19, 6, v19
	v_ashrrev_i32_e32 v20, 6, v20
	v_ashrrev_i32_e32 v21, 6, v21
	v_ashrrev_i32_e32 v22, 6, v22
	v_ashrrev_i32_e32 v23, 6, v23
	v_ashrrev_i32_e32 v24, 6, v24
	v_ashrrev_i32_e32 v25, 6, v25
	v_ashrrev_i32_e32 v26, 6, v26
	v_ashrrev_i32_e32 v27, 6, v27
	v_ashrrev_i32_e32 v28, 6, v28
	v_ashrrev_i32_e32 v29, 6, v29
	v_ashrrev_i32_e32 v30, 6, v30
	v_ashrrev_i32_e32 v31, 4, v35
	v_ashrrev_i32_e32 v93, 4, v7
	v_ashrrev_i32_e32 v94, 4, v9
	v_ashrrev_i32_e32 v95, 4, v17
	v_mul_lo_u32 v4, v10, s4
	v_writelane_b32 v255, s1, 10
	v_mul_lo_u32 v14, v49, s6
	v_add_u32_e32 v3, 0, v3
	v_mul_lo_u32 v2, v2, s85
	v_mul_lo_u32 v8, v8, s85
	v_mul_lo_u32 v16, v16, s85
	v_mul_lo_u32 v18, v18, s85
	v_mul_lo_u32 v19, v19, s85
	v_mul_lo_u32 v20, v20, s85
	v_mul_lo_u32 v21, v21, s85
	v_mul_lo_u32 v22, v22, s85
	v_mul_lo_u32 v23, v23, s85
	v_mul_lo_u32 v24, v24, s85
	v_mul_lo_u32 v25, v25, s85
	v_mul_lo_u32 v26, v26, s85
	v_mul_lo_u32 v27, v27, s85
	v_mul_lo_u32 v28, v28, s85
	v_mul_lo_u32 v29, v29, s85
	v_mul_lo_u32 v30, v30, s85
	v_mul_lo_u32 v31, v31, s85
	v_mul_lo_u32 v7, v93, s85
	v_mul_lo_u32 v9, v94, s85
	v_mul_lo_u32 v17, v95, s85
	v_add_u32_e32 v12, 0, v12
	v_add_u32_e32 v56, 0x400, v36
	v_add_u32_e32 v58, 0x800, v36
	v_add_u32_e32 v60, 0xc00, v36
	v_or_b32_e32 v118, 2, v87
	v_or_b32_e32 v120, 3, v87
	v_or_b32_e32 v122, 4, v87
	v_or_b32_e32 v124, 5, v87
	v_or_b32_e32 v126, 6, v87
	v_or_b32_e32 v128, 7, v87
	v_readlane_b32 s5, v254, 6
	v_mad_u32_u24 v4, v34, s6, v4
	v_writelane_b32 v255, s68, 31
	v_cmp_gt_u32_e64 s[36:37], 64, v35
	v_mul_lo_u32 v86, v49, s85
	v_add_u32_e32 v88, s84, v36
	v_or_b32_e32 v90, 32, v41
	v_ashrrev_i32_e32 v37, 31, v36
	v_add_u32_e32 v96, 0xc300, v12
	v_ashrrev_i32_e32 v57, 31, v56
	v_add_u32_e32 v97, 0xd300, v12
	v_ashrrev_i32_e32 v59, 31, v58
	v_add_u32_e32 v98, 0xe300, v12
	v_ashrrev_i32_e32 v61, 31, v60
	v_add_u32_e32 v99, 0xf300, v12
	v_or_b32_e32 v100, 1, v45
	v_or_b32_e32 v101, 2, v45
	v_or_b32_e32 v102, 3, v45
	v_or_b32_e32 v103, 8, v45
	v_or_b32_e32 v104, 9, v45
	v_or_b32_e32 v105, 10, v45
	v_or_b32_e32 v106, 11, v45
	v_or_b32_e32 v107, 16, v45
	v_or_b32_e32 v108, 17, v45
	v_or_b32_e32 v109, 18, v45
	v_or_b32_e32 v110, 19, v45
	v_or_b32_e32 v111, 24, v45
	v_or_b32_e32 v112, 25, v45
	v_or_b32_e32 v113, 26, v45
	v_or_b32_e32 v114, 27, v45
	v_sub_u32_e32 v115, 63, v87
	v_sub_u32_e32 v117, 63, v116
	v_sub_u32_e32 v119, 63, v118
	v_sub_u32_e32 v121, 63, v120
	v_sub_u32_e32 v123, 63, v122
	v_sub_u32_e32 v125, 63, v124
	v_sub_u32_e32 v127, 63, v126
	v_sub_u32_e32 v129, 63, v128
	v_cmp_lt_i32_e64 s[20:21], 0, v5
	v_cmp_lt_i32_e64 s[96:97], 1, v5
	v_cmp_lt_i32_e64 s[94:95], 2, v5
	v_cmp_lt_i32_e64 s[88:89], 3, v5
	v_cmp_lt_i32_e64 s[34:35], 4, v5
	v_cmp_lt_i32_e64 s[28:29], 5, v5
	v_cmp_lt_i32_e64 s[30:31], 6, v5
	v_cmp_lt_i32_e64 s[38:39], 7, v5
	v_add_u32_e32 v63, 0x84, v64
	v_add_u32_e32 v65, 0x108, v64
	v_add_u32_e32 v132, 0x18c, v64
	v_add_u32_e32 v133, 0x210, v64
	v_add_u32_e32 v134, 0x294, v64
	v_add_u32_e32 v135, 0x318, v64
	v_add_u32_e32 v66, s5, v13
	v_add3_u32 v208, v4, v13, s5
	v_add_u32_e32 v209, v11, v2
	v_add_u32_e32 v210, v11, v8
	v_add_u32_e32 v211, v11, v16
	v_add_u32_e32 v212, v11, v18
	v_add_u32_e32 v213, v11, v19
	v_add_u32_e32 v214, v11, v20
	v_add_u32_e32 v215, v11, v21
	v_add_u32_e32 v216, v11, v22
	v_add_u32_e32 v217, v11, v23
	v_add_u32_e32 v218, v11, v24
	v_add_u32_e32 v219, v11, v25
	v_add_u32_e32 v220, v11, v26
	v_add_u32_e32 v221, v11, v27
	v_add_u32_e32 v222, v11, v28
	v_add_u32_e32 v223, v11, v29
	v_add_u32_e32 v224, v11, v30
	v_add_u32_e32 v225, v40, v31
	v_add_u32_e32 v226, v40, v7
	v_add_u32_e32 v227, v40, v9
	v_add_u32_e32 v228, v40, v17
	v_lshlrev_b32_e32 v68, 2, v34
	v_add_u32_e32 v229, v42, v14
	v_add_u32_e32 v230, v3, v6
	v_writelane_b32 v255, s69, 32
	s_branch .LBB0_99

.LBB0_102:
	s_or_b64 exec, exec, vcc
	v_lshlrev_b32_e32 v22, 2, v78
	v_add_u32_e32 v18, v69, v44
	v_add_u32_e32 v23, v22, v45
	v_lshlrev_b32_e32 v19, 2, v18
	v_mul_lo_u32 v20, v23, s85
	v_cmp_le_i32_e32 vcc, v18, v23
	v_add3_u32 v19, 0, v19, v20
	v_or_b32_e32 v20, 1, v23
	s_nop 6
	v_cndmask_b32_e32 v2, 0, v2, vcc
	v_cmp_le_i32_e32 vcc, v18, v20
	v_add_u32_e32 v20, 0x4000, v19
	s_lshl_b64 s[0:1], s[92:93], 13
	v_cndmask_b32_e32 v3, 0, v3, vcc
	ds_write2_b32 v20, v2, v3 offset0:64 offset1:129
	v_or_b32_e32 v2, 2, v23
	v_cmp_le_i32_e32 vcc, v18, v2
	v_or_b32_e32 v3, 3, v23
	v_add_u32_e32 v25, 0x8000, v229
	v_cndmask_b32_e32 v2, 0, v4, vcc
	v_cmp_le_i32_e32 vcc, v18, v3
	v_add_u32_e32 v4, 0x4200, v19
	s_mov_b32 s11, s93
	v_cndmask_b32_e32 v3, 0, v5, vcc
	ds_write2_b32 v4, v2, v3 offset0:66 offset1:131
	v_add_u32_e32 v2, 8, v23
	v_cmp_le_i32_e32 vcc, v18, v2
	v_add_u32_e32 v3, 9, v23
	v_add_u32_e32 v4, 0x4800, v19
	v_cndmask_b32_e32 v2, 0, v6, vcc
	v_cmp_le_i32_e32 vcc, v18, v3
	v_mov_b32_e32 v69, v131
	v_add_u32_e32 v27, v22, v104
	v_cndmask_b32_e32 v3, 0, v7, vcc
	ds_write2_b32 v4, v2, v3 offset0:72 offset1:137
	v_add_u32_e32 v2, 10, v23
	v_cmp_le_i32_e32 vcc, v18, v2
	v_add_u32_e32 v3, 11, v23
	v_add_u32_e32 v4, 0x4a00, v19
	v_cndmask_b32_e32 v2, 0, v8, vcc
	v_cmp_le_i32_e32 vcc, v18, v3
	v_add_u32_e32 v28, v22, v105
	v_add_u32_e32 v29, v22, v106
	v_cndmask_b32_e32 v3, 0, v9, vcc
	ds_write2_b32 v4, v2, v3 offset0:74 offset1:139
	v_add_u32_e32 v2, 16, v23
	v_cmp_le_i32_e32 vcc, v18, v2
	v_add_u32_e32 v3, 17, v23
	v_add_u32_e32 v4, 0x5000, v19
	v_cndmask_b32_e32 v2, 0, v10, vcc
	v_cmp_le_i32_e32 vcc, v18, v3
	v_add_u32_e32 v30, v22, v107
	v_add_u32_e32 v31, v22, v108
	v_cndmask_b32_e32 v3, 0, v11, vcc
	ds_write2_b32 v4, v2, v3 offset0:80 offset1:145
	v_add_u32_e32 v2, 18, v23
	v_cmp_le_i32_e32 vcc, v18, v2
	v_add_u32_e32 v3, 19, v23
	v_add_u32_e32 v4, 0x5200, v19
	v_cndmask_b32_e32 v2, 0, v12, vcc
	v_cmp_le_i32_e32 vcc, v18, v3
	v_add_u32_e32 v32, v22, v109
	v_add_u32_e32 v33, v22, v110
	v_cndmask_b32_e32 v3, 0, v13, vcc
	ds_write2_b32 v4, v2, v3 offset0:82 offset1:147
	v_add_u32_e32 v2, 24, v23
	v_cmp_le_i32_e32 vcc, v18, v2
	v_add_u32_e32 v3, 25, v23
	v_add_u32_e32 v4, 0x5800, v19
	v_cndmask_b32_e32 v2, 0, v14, vcc
	v_cmp_le_i32_e32 vcc, v18, v3
	v_add_u32_e32 v76, v22, v112
	v_add_u32_e32 v77, v22, v113
	v_cndmask_b32_e32 v3, 0, v15, vcc
	ds_write2_b32 v4, v2, v3 offset0:88 offset1:153
	v_add_u32_e32 v2, 26, v23
	v_cmp_le_i32_e32 vcc, v18, v2
	v_add_u32_e32 v3, 27, v23
	v_add_u32_e32 v4, 0x5a00, v19
	v_cndmask_b32_e32 v2, 0, v16, vcc
	v_cmp_le_i32_e32 vcc, v18, v3
	v_lshl_add_u64 v[18:19], v[52:53], 0, s[0:1]
	s_nop 0
	v_cndmask_b32_e32 v3, 0, v17, vcc
	ds_write2_b32 v4, v2, v3 offset0:90 offset1:155
	s_waitcnt lgkmcnt(0)
	s_barrier
	s_waitcnt vmcnt(0)
	v_add_u32_e32 v192, v42, v86
	v_add_u32_e32 v192, 0x4000, v192
	ds_read2_b32 v[18:19], v25 offset0:128 offset1:130
	ds_read2_b32 v[20:21], v25 offset0:132 offset1:134
	ds_read2_b32 v[188:189], v25 offset0:136 offset1:138
	ds_read2_b32 v[190:191], v25 offset0:140 offset1:142
	s_waitcnt lgkmcnt(3)
	v_mfma_f32_32x32x2_f32 v[2:17], v18, v136, 0
	v_mfma_f32_32x32x2_f32 v[2:17], v19, v137, v[2:17]
	ds_read2_b32 v[18:19], v25 offset0:144 offset1:146
	s_waitcnt lgkmcnt(3)
	v_mfma_f32_32x32x2_f32 v[2:17], v20, v138, v[2:17]
	v_mfma_f32_32x32x2_f32 v[2:17], v21, v139, v[2:17]
	ds_read2_b32 v[20:21], v25 offset0:148 offset1:150
	s_waitcnt lgkmcnt(3)
	v_mfma_f32_32x32x2_f32 v[2:17], v188, v140, v[2:17]
	v_mfma_f32_32x32x2_f32 v[2:17], v189, v141, v[2:17]
	ds_read2_b32 v[188:189], v25 offset0:152 offset1:154
	s_waitcnt lgkmcnt(3)
	v_mfma_f32_32x32x2_f32 v[2:17], v190, v142, v[2:17]
	v_mfma_f32_32x32x2_f32 v[2:17], v191, v143, v[2:17]
	ds_read2_b32 v[190:191], v25 offset0:156 offset1:158
	s_waitcnt lgkmcnt(3)
	v_mfma_f32_32x32x2_f32 v[2:17], v18, v144, v[2:17]
	v_mfma_f32_32x32x2_f32 v[2:17], v19, v145, v[2:17]
	ds_read2_b32 v[18:19], v192 offset0:64 offset1:66
	s_waitcnt lgkmcnt(3)
	v_mfma_f32_32x32x2_f32 v[2:17], v20, v146, v[2:17]
	v_mfma_f32_32x32x2_f32 v[2:17], v21, v147, v[2:17]
	ds_read2_b32 v[20:21], v192 offset0:68 offset1:70
	s_waitcnt lgkmcnt(3)
	v_mfma_f32_32x32x2_f32 v[2:17], v188, v148, v[2:17]
	v_mfma_f32_32x32x2_f32 v[2:17], v189, v149, v[2:17]
	ds_read2_b32 v[188:189], v192 offset0:72 offset1:74
	s_waitcnt lgkmcnt(3)
	v_mfma_f32_32x32x2_f32 v[2:17], v190, v150, v[2:17]
	v_mfma_f32_32x32x2_f32 v[2:17], v191, v151, v[2:17]
	ds_read2_b32 v[190:191], v192 offset0:76 offset1:78
	s_waitcnt lgkmcnt(3)
	v_mfma_f32_32x32x2_f32 v[2:17], v18, v152, v[2:17]
	v_mfma_f32_32x32x2_f32 v[2:17], v19, v153, v[2:17]
	ds_read2_b32 v[18:19], v192 offset0:80 offset1:82
	s_waitcnt lgkmcnt(3)
	v_mfma_f32_32x32x2_f32 v[2:17], v20, v154, v[2:17]
	v_mfma_f32_32x32x2_f32 v[2:17], v21, v155, v[2:17]
	ds_read2_b32 v[20:21], v192 offset0:84 offset1:86
	s_waitcnt lgkmcnt(3)
	v_mfma_f32_32x32x2_f32 v[2:17], v188, v156, v[2:17]
	v_mfma_f32_32x32x2_f32 v[2:17], v189, v157, v[2:17]
	ds_read2_b32 v[188:189], v192 offset0:88 offset1:90
	s_waitcnt lgkmcnt(3)
	v_mfma_f32_32x32x2_f32 v[2:17], v190, v158, v[2:17]
	v_mfma_f32_32x32x2_f32 v[2:17], v191, v159, v[2:17]
	ds_read2_b32 v[190:191], v192 offset0:92 offset1:94
	s_waitcnt lgkmcnt(3)
	v_mfma_f32_32x32x2_f32 v[2:17], v18, v160, v[2:17]
	v_mfma_f32_32x32x2_f32 v[2:17], v19, v161, v[2:17]
	ds_read2_b32 v[18:19], v192 offset0:96 offset1:98
	s_waitcnt lgkmcnt(3)
	v_mfma_f32_32x32x2_f32 v[2:17], v20, v162, v[2:17]
	v_mfma_f32_32x32x2_f32 v[2:17], v21, v163, v[2:17]
	ds_read2_b32 v[20:21], v192 offset0:100 offset1:102
	s_waitcnt lgkmcnt(3)
	v_mfma_f32_32x32x2_f32 v[2:17], v188, v164, v[2:17]
	v_mfma_f32_32x32x2_f32 v[2:17], v189, v165, v[2:17]
	ds_read2_b32 v[188:189], v192 offset0:104 offset1:106
	s_waitcnt lgkmcnt(3)
	v_mfma_f32_32x32x2_f32 v[2:17], v190, v166, v[2:17]
	v_mfma_f32_32x32x2_f32 v[2:17], v191, v167, v[2:17]
	ds_read2_b32 v[190:191], v192 offset0:108 offset1:110
	s_waitcnt lgkmcnt(3)
	v_mfma_f32_32x32x2_f32 v[2:17], v18, v168, v[2:17]
	v_mfma_f32_32x32x2_f32 v[2:17], v19, v169, v[2:17]
	ds_read2_b32 v[18:19], v192 offset0:112 offset1:114
	s_waitcnt lgkmcnt(3)
	v_mfma_f32_32x32x2_f32 v[2:17], v20, v170, v[2:17]
	v_mfma_f32_32x32x2_f32 v[2:17], v21, v171, v[2:17]
	ds_read2_b32 v[20:21], v192 offset0:116 offset1:118
	s_waitcnt lgkmcnt(3)
	v_mfma_f32_32x32x2_f32 v[2:17], v188, v172, v[2:17]
	v_mfma_f32_32x32x2_f32 v[2:17], v189, v173, v[2:17]
	ds_read2_b32 v[188:189], v192 offset0:120 offset1:122
	s_waitcnt lgkmcnt(3)
	v_mfma_f32_32x32x2_f32 v[2:17], v190, v174, v[2:17]
	v_mfma_f32_32x32x2_f32 v[2:17], v191, v175, v[2:17]
	ds_read2_b32 v[190:191], v192 offset0:124 offset1:126
	s_waitcnt lgkmcnt(3)
	v_mfma_f32_32x32x2_f32 v[2:17], v18, v176, v[2:17]
	v_mfma_f32_32x32x2_f32 v[2:17], v19, v177, v[2:17]
	s_waitcnt lgkmcnt(2)
	v_mfma_f32_32x32x2_f32 v[2:17], v20, v178, v[2:17]
	v_mfma_f32_32x32x2_f32 v[2:17], v21, v179, v[2:17]
	s_waitcnt lgkmcnt(1)
	v_mfma_f32_32x32x2_f32 v[2:17], v188, v180, v[2:17]
	v_mfma_f32_32x32x2_f32 v[2:17], v189, v181, v[2:17]
	s_waitcnt lgkmcnt(0)
	v_mfma_f32_32x32x2_f32 v[2:17], v190, v182, v[2:17]
	v_mfma_f32_32x32x2_f32 v[2:17], v191, v183, v[2:17]
	v_add_u32_e32 v26, v22, v103
	v_add_u32_e32 v25, v22, v102
	v_add_u32_e32 v69, v22, v111
	v_add_u32_e32 v20, v22, v100
	v_add_u32_e32 v24, v22, v101
	v_sub_u32_e32 v18, 63, v23
	v_cndmask_b32_e64 v18, v18, v23, s[6:7]
	v_mad_u64_u32 v[18:19], s[0:1], v18, s85, v[48:49]
	ds_read_b32 v19, v18
	v_sub_u32_e32 v21, 63, v20
	v_cndmask_b32_e64 v20, v21, v20, s[6:7]
	v_mad_u64_u32 v[20:21], s[0:1], v20, s85, v[48:49]
	s_waitcnt lgkmcnt(0)
	s_nop 9
	v_add_f32_e32 v2, v2, v19
	ds_write_b32 v18, v2
	ds_read_b32 v2, v20
	v_sub_u32_e32 v18, 63, v24
	v_cndmask_b32_e64 v18, v18, v24, s[6:7]
	v_mad_u64_u32 v[18:19], s[0:1], v18, s85, v[48:49]
	s_waitcnt lgkmcnt(0)
	v_add_f32_e32 v2, v3, v2
	ds_write_b32 v20, v2
	ds_read_b32 v19, v18
	v_sub_u32_e32 v2, 63, v25
	v_cndmask_b32_e64 v2, v2, v25, s[6:7]
	v_mad_u64_u32 v[2:3], s[0:1], v2, s85, v[48:49]
	s_waitcnt lgkmcnt(0)
	v_add_f32_e32 v3, v4, v19
	ds_write_b32 v18, v3
	ds_read_b32 v3, v2
	v_sub_u32_e32 v4, 63, v26
	v_cndmask_b32_e64 v4, v4, v26, s[6:7]
	v_mad_u64_u32 v[18:19], s[0:1], v4, s85, v[48:49]
	s_waitcnt lgkmcnt(0)
	v_add_f32_e32 v3, v5, v3
	ds_write_b32 v2, v3
	ds_read_b32 v4, v18
	v_sub_u32_e32 v2, 63, v27
	v_cndmask_b32_e64 v2, v2, v27, s[6:7]
	v_mad_u64_u32 v[2:3], s[0:1], v2, s85, v[48:49]
	s_waitcnt lgkmcnt(0)
	v_add_f32_e32 v3, v6, v4
	ds_write_b32 v18, v3
	ds_read_b32 v3, v2
	v_sub_u32_e32 v4, 63, v28
	v_cndmask_b32_e64 v4, v4, v28, s[6:7]
	v_mad_u64_u32 v[4:5], s[0:1], v4, s85, v[48:49]
	s_waitcnt lgkmcnt(0)
	v_add_f32_e32 v3, v7, v3
	ds_write_b32 v2, v3
	ds_read_b32 v5, v4
	v_sub_u32_e32 v2, 63, v29
	v_cndmask_b32_e64 v2, v2, v29, s[6:7]
	v_mad_u64_u32 v[2:3], s[0:1], v2, s85, v[48:49]
	s_waitcnt lgkmcnt(0)
	v_add_f32_e32 v3, v8, v5
	ds_write_b32 v4, v3
	ds_read_b32 v3, v2
	v_sub_u32_e32 v4, 63, v30
	v_cndmask_b32_e64 v4, v4, v30, s[6:7]
	v_mad_u64_u32 v[4:5], s[0:1], v4, s85, v[48:49]
	s_waitcnt lgkmcnt(0)
	v_add_f32_e32 v3, v9, v3
	ds_write_b32 v2, v3
	ds_read_b32 v5, v4
	v_sub_u32_e32 v2, 63, v31
	v_cndmask_b32_e64 v2, v2, v31, s[6:7]
	v_mad_u64_u32 v[2:3], s[0:1], v2, s85, v[48:49]
	s_waitcnt lgkmcnt(0)
	v_add_f32_e32 v3, v10, v5
	ds_write_b32 v4, v3
	ds_read_b32 v3, v2
	v_sub_u32_e32 v4, 63, v32
	v_cndmask_b32_e64 v4, v4, v32, s[6:7]
	v_mad_u64_u32 v[4:5], s[0:1], v4, s85, v[48:49]
	s_waitcnt lgkmcnt(0)
	v_add_f32_e32 v3, v11, v3
	ds_write_b32 v2, v3
	ds_read_b32 v5, v4
	v_sub_u32_e32 v2, 63, v33
	v_cndmask_b32_e64 v2, v2, v33, s[6:7]
	v_mad_u64_u32 v[2:3], s[0:1], v2, s85, v[48:49]
	s_waitcnt lgkmcnt(0)
	v_add_f32_e32 v3, v12, v5
	ds_write_b32 v4, v3
	ds_read_b32 v3, v2
	v_sub_u32_e32 v4, 63, v69
	v_cndmask_b32_e64 v4, v4, v69, s[6:7]
	v_mad_u64_u32 v[4:5], s[0:1], v4, s85, v[48:49]
	s_waitcnt lgkmcnt(0)
	v_add_f32_e32 v3, v13, v3
	ds_write_b32 v2, v3
	ds_read_b32 v5, v4
	v_sub_u32_e32 v2, 63, v76
	v_cndmask_b32_e64 v2, v2, v76, s[6:7]
	v_mad_u64_u32 v[2:3], s[0:1], v2, s85, v[48:49]
	s_waitcnt lgkmcnt(0)
	v_add_f32_e32 v3, v14, v5
	ds_write_b32 v4, v3
	ds_read_b32 v3, v2
	v_sub_u32_e32 v4, 63, v77
	v_cndmask_b32_e64 v4, v4, v77, s[6:7]
	v_mad_u64_u32 v[4:5], s[0:1], v4, s85, v[48:49]
	s_waitcnt lgkmcnt(0)
	v_add_f32_e32 v3, v15, v3
	ds_write_b32 v2, v3
	ds_read_b32 v2, v4
	v_add_u32_e32 v3, v22, v114
	v_sub_u32_e32 v5, 63, v3
	v_cndmask_b32_e64 v3, v5, v3, s[6:7]
	s_waitcnt lgkmcnt(0)
	v_add_f32_e32 v2, v16, v2
	ds_write_b32 v4, v2
	v_mad_u64_u32 v[2:3], s[0:1], v3, s85, v[48:49]
	ds_read_b32 v3, v2
	s_waitcnt lgkmcnt(0)
	v_add_f32_e32 v3, v17, v3
	ds_write_b32 v2, v3

.LBB0_145:
	s_and_b64 vcc, exec, s[0:1]
	s_cbranch_vccz .LBB0_103
	v_cndmask_b32_e64 v2, v115, v87, s[6:7]
	v_add_u32_e32 v16, s25, v2
	s_lshl_b32 s0, s11, 7
	s_mov_b32 s1, s93
	v_ashrrev_i32_e32 v17, 31, v16
	v_lshl_add_u64 v[18:19], s[0:1], 2, v[70:71]
	v_lshlrev_b64 v[2:3], 10, v[16:17]
	v_lshl_add_u64 v[2:3], v[18:19], 0, v[2:3]
	global_load_dword v17, v[2:3], off
	v_cndmask_b32_e64 v2, v117, v116, s[6:7]
	v_add_u32_e32 v14, s25, v2
	v_ashrrev_i32_e32 v15, 31, v14
	v_lshlrev_b64 v[2:3], 10, v[14:15]
	v_lshl_add_u64 v[2:3], v[18:19], 0, v[2:3]
	global_load_dword v15, v[2:3], off
	v_cndmask_b32_e64 v2, v119, v118, s[6:7]
	v_add_u32_e32 v12, s25, v2
	v_ashrrev_i32_e32 v13, 31, v12
	v_lshlrev_b64 v[2:3], 10, v[12:13]
	v_lshl_add_u64 v[2:3], v[18:19], 0, v[2:3]
	global_load_dword v13, v[2:3], off
	v_cndmask_b32_e64 v2, v121, v120, s[6:7]
	v_add_u32_e32 v10, s25, v2
	v_ashrrev_i32_e32 v11, 31, v10
	v_lshlrev_b64 v[2:3], 10, v[10:11]
	v_lshl_add_u64 v[2:3], v[18:19], 0, v[2:3]
	global_load_dword v11, v[2:3], off
	v_cndmask_b32_e64 v2, v123, v122, s[6:7]
	v_add_u32_e32 v8, s25, v2
	v_ashrrev_i32_e32 v9, 31, v8
	v_lshlrev_b64 v[2:3], 10, v[8:9]
	v_lshl_add_u64 v[2:3], v[18:19], 0, v[2:3]
	global_load_dword v9, v[2:3], off
	v_cndmask_b32_e64 v2, v125, v124, s[6:7]
	v_add_u32_e32 v6, s25, v2
	v_ashrrev_i32_e32 v7, 31, v6
	v_lshlrev_b64 v[2:3], 10, v[6:7]
	v_lshl_add_u64 v[2:3], v[18:19], 0, v[2:3]
	global_load_dword v7, v[2:3], off
	v_cndmask_b32_e64 v2, v127, v126, s[6:7]
	v_add_u32_e32 v4, s25, v2
	v_ashrrev_i32_e32 v5, 31, v4
	v_lshlrev_b64 v[2:3], 10, v[4:5]
	v_lshl_add_u64 v[2:3], v[18:19], 0, v[2:3]
	global_load_dword v5, v[2:3], off
	v_cndmask_b32_e64 v2, v129, v128, s[6:7]
	v_add_u32_e32 v2, s25, v2
	v_ashrrev_i32_e32 v3, 31, v2
	v_lshlrev_b64 v[20:21], 10, v[2:3]
	v_lshl_add_u64 v[18:19], v[18:19], 0, v[20:21]
	global_load_dword v19, v[18:19], off
	v_mad_i64_i32 v[188:189], vcc, v16, s15, v[72:73]
	global_load_dword v22, v[188:189], off offset:3072
	global_load_dword v23, v[188:189], off offset:3584
	v_mad_i64_i32 v[190:191], vcc, v14, s15, v[72:73]
	global_load_dword v24, v[190:191], off offset:3072
	global_load_dword v25, v[190:191], off offset:3584
	v_mad_i64_i32 v[188:189], vcc, v12, s15, v[72:73]
	global_load_dword v26, v[188:189], off offset:3072
	global_load_dword v27, v[188:189], off offset:3584
	v_mad_i64_i32 v[190:191], vcc, v10, s15, v[72:73]
	global_load_dword v28, v[190:191], off offset:3072
	global_load_dword v29, v[190:191], off offset:3584
	v_mad_i64_i32 v[188:189], vcc, v8, s15, v[72:73]
	global_load_dword v30, v[188:189], off offset:3072
	global_load_dword v31, v[188:189], off offset:3584
	v_mad_i64_i32 v[190:191], vcc, v6, s15, v[72:73]
	global_load_dword v32, v[190:191], off offset:3072
	global_load_dword v33, v[190:191], off offset:3584
	v_mad_i64_i32 v[188:189], vcc, v4, s15, v[72:73]
	global_load_dword v184, v[188:189], off offset:3072
	global_load_dword v185, v[188:189], off offset:3584
	v_mad_i64_i32 v[190:191], vcc, v2, s15, v[72:73]
	global_load_dword v186, v[190:191], off offset:3072
	global_load_dword v187, v[190:191], off offset:3584
	s_lshl_b64 s[0:1], s[92:93], 13
	v_lshl_add_u64 v[192:193], v[52:53], 0, s[0:1]
	global_load_dword v136, v[192:193], off
	global_load_dword v137, v[192:193], off offset:512
	global_load_dword v138, v[192:193], off offset:1024
	global_load_dword v139, v[192:193], off offset:1536
	global_load_dword v140, v[192:193], off offset:2048
	global_load_dword v141, v[192:193], off offset:2560
	global_load_dword v142, v[192:193], off offset:3072
	global_load_dword v143, v[192:193], off offset:3584
	s_mov_b64 s[0:1], 0x1000
	v_lshl_add_u64 v[192:193], v[192:193], 0, s[0:1]
	global_load_dword v144, v[192:193], off
	global_load_dword v145, v[192:193], off offset:512
	global_load_dword v146, v[192:193], off offset:1024
	global_load_dword v147, v[192:193], off offset:1536
	global_load_dword v148, v[192:193], off offset:2048
	global_load_dword v149, v[192:193], off offset:2560
	global_load_dword v150, v[192:193], off offset:3072
	global_load_dword v151, v[192:193], off offset:3584
	v_mov_b32_e32 v3, 0
	s_waitcnt vmcnt(39)
	v_add_f32_e32 v18, 0, v17
	s_waitcnt vmcnt(38)
	v_add_f32_e32 v17, v18, v15
	s_waitcnt vmcnt(37)
	v_add_f32_e32 v15, v17, v13
	s_waitcnt vmcnt(36)
	v_add_f32_e32 v13, v15, v11
	s_waitcnt vmcnt(35)
	v_add_f32_e32 v11, v13, v9
	s_waitcnt vmcnt(34)
	v_add_f32_e32 v9, v11, v7
	s_waitcnt vmcnt(33)
	v_add_f32_e32 v7, v9, v5
	s_waitcnt vmcnt(32)
	v_add_f32_e32 v5, v7, v19
	ds_write_b32 v88, v5
	s_waitcnt vmcnt(31)
	s_mul_i32 s0, s25, 0x28c0
	s_lshl_b32 s1, s22, 2
	s_add_u32 s0, s0, s1
	s_add_u32 s0, s0, 0x1000
	s_add_u32 s0, s8, s0
	s_addc_u32 s1, s9, 0
	s_mov_b32 s100, 0x5180
	s_mov_b32 s101, 0
	s_cmp_eq_u32 s11, 0
	s_cbranch_scc1 .Lgla_out_fwd
	s_mov_b32 s100, 0xffffae80
	s_mov_b32 s101, -1
.Lgla_out_fwd:
	v_xor_b32_e32 v194, 63, v41
	v_cndmask_b32_e64 v194, v194, v41, s[6:7]
	v_mul_u32_u24_e32 v194, 0x28c0, v194
	v_add_u32_e32 v194, v194, v68
	v_lshl_add_u32 v194, v44, 2, v194
	v_mov_b32_e32 v195, 0
	v_lshl_add_u64 v[194:195], s[0:1], 0, v[194:195]
	global_load_dword v152, v[194:195], off
	v_lshl_add_u64 v[194:195], v[194:195], 0, s[100:101]
	global_load_dword v153, v[194:195], off
	v_lshl_add_u64 v[194:195], v[194:195], 0, s[100:101]
	global_load_dword v154, v[194:195], off
	v_lshl_add_u64 v[194:195], v[194:195], 0, s[100:101]
	global_load_dword v155, v[194:195], off
	v_lshl_add_u64 v[194:195], v[194:195], 0, s[100:101]
	global_load_dword v156, v[194:195], off
	v_lshl_add_u64 v[194:195], v[194:195], 0, s[100:101]
	global_load_dword v157, v[194:195], off
	v_lshl_add_u64 v[194:195], v[194:195], 0, s[100:101]
	global_load_dword v158, v[194:195], off
	v_lshl_add_u64 v[194:195], v[194:195], 0, s[100:101]
	global_load_dword v159, v[194:195], off
	v_lshl_add_u64 v[194:195], v[194:195], 0, s[100:101]
	global_load_dword v160, v[194:195], off
	v_lshl_add_u64 v[194:195], v[194:195], 0, s[100:101]
	global_load_dword v161, v[194:195], off
	v_lshl_add_u64 v[194:195], v[194:195], 0, s[100:101]
	global_load_dword v162, v[194:195], off
	v_lshl_add_u64 v[194:195], v[194:195], 0, s[100:101]
	global_load_dword v163, v[194:195], off
	v_lshl_add_u64 v[194:195], v[194:195], 0, s[100:101]
	global_load_dword v164, v[194:195], off
	v_lshl_add_u64 v[194:195], v[194:195], 0, s[100:101]
	global_load_dword v165, v[194:195], off
	v_lshl_add_u64 v[194:195], v[194:195], 0, s[100:101]
	global_load_dword v166, v[194:195], off
	v_lshl_add_u64 v[194:195], v[194:195], 0, s[100:101]
	global_load_dword v167, v[194:195], off
	v_lshl_add_u64 v[194:195], v[194:195], 0, s[100:101]
	global_load_dword v168, v[194:195], off
	v_lshl_add_u64 v[194:195], v[194:195], 0, s[100:101]
	global_load_dword v169, v[194:195], off
	v_lshl_add_u64 v[194:195], v[194:195], 0, s[100:101]
	global_load_dword v170, v[194:195], off
	v_lshl_add_u64 v[194:195], v[194:195], 0, s[100:101]
	global_load_dword v171, v[194:195], off
	v_lshl_add_u64 v[194:195], v[194:195], 0, s[100:101]
	global_load_dword v172, v[194:195], off
	v_lshl_add_u64 v[194:195], v[194:195], 0, s[100:101]
	global_load_dword v173, v[194:195], off
	v_lshl_add_u64 v[194:195], v[194:195], 0, s[100:101]
	global_load_dword v174, v[194:195], off
	v_lshl_add_u64 v[194:195], v[194:195], 0, s[100:101]
	global_load_dword v175, v[194:195], off
	v_lshl_add_u64 v[194:195], v[194:195], 0, s[100:101]
	global_load_dword v176, v[194:195], off
	v_lshl_add_u64 v[194:195], v[194:195], 0, s[100:101]
	global_load_dword v177, v[194:195], off
	v_lshl_add_u64 v[194:195], v[194:195], 0, s[100:101]
	global_load_dword v178, v[194:195], off
	v_lshl_add_u64 v[194:195], v[194:195], 0, s[100:101]
	global_load_dword v179, v[194:195], off
	v_lshl_add_u64 v[194:195], v[194:195], 0, s[100:101]
	global_load_dword v180, v[194:195], off
	v_lshl_add_u64 v[194:195], v[194:195], 0, s[100:101]
	global_load_dword v181, v[194:195], off
	v_lshl_add_u64 v[194:195], v[194:195], 0, s[100:101]
	global_load_dword v182, v[194:195], off
	v_lshl_add_u64 v[194:195], v[194:195], 0, s[100:101]
	global_load_dword v183, v[194:195], off
	s_waitcnt lgkmcnt(0)
	s_barrier
	s_and_saveexec_b64 s[0:1], s[20:21]
	s_cbranch_execz .LBB0_154
	ds_read_b32 v3, v89
	s_waitcnt lgkmcnt(0)
	v_add_f32_e32 v3, 0, v3
	s_or_b64 exec, exec, s[0:1]
	s_and_saveexec_b64 s[0:1], s[96:97]
	s_cbranch_execnz .LBB0_155

.LBB0_162:
	s_or_b64 exec, exec, s[0:1]
	v_add_f32_e32 v20, v18, v3
	v_mul_f32_e32 v21, 0x3fb8aa3b, v20
	v_mul_f32_e32 v20, 0xbfb8aa3b, v20
	v_exp_f32_e32 v21, v21
	v_exp_f32_e32 v20, v20
	s_waitcnt vmcnt(62)
	v_mul_f32_e32 v22, 0x3e3504f3, v22
	v_mul_f32_e32 v22, v22, v21
	v_mul_f32_e32 v23, v23, v20
	ds_write2st64_b32 v62, v22, v23 offset0:130 offset1:195
	v_add_f32_e32 v20, v17, v3
	v_mul_f32_e32 v21, 0x3fb8aa3b, v20
	v_mul_f32_e32 v20, 0xbfb8aa3b, v20
	v_exp_f32_e32 v21, v21
	v_exp_f32_e32 v20, v20
	s_waitcnt vmcnt(60)
	v_mul_f32_e32 v24, 0x3e3504f3, v24
	v_mul_f32_e32 v24, v24, v21
	v_mul_f32_e32 v25, v25, v20
	ds_write2st64_b32 v64, v24, v25 offset0:130 offset1:195
	v_add_f32_e32 v20, v15, v3
	v_mul_f32_e32 v21, 0x3fb8aa3b, v20
	v_mul_f32_e32 v20, 0xbfb8aa3b, v20
	v_exp_f32_e32 v21, v21
	v_exp_f32_e32 v20, v20
	s_waitcnt vmcnt(58)
	v_mul_f32_e32 v26, 0x3e3504f3, v26
	v_mul_f32_e32 v26, v26, v21
	v_mul_f32_e32 v27, v27, v20
	ds_write2st64_b32 v63, v26, v27 offset0:130 offset1:195
	v_add_f32_e32 v20, v13, v3
	v_mul_f32_e32 v21, 0x3fb8aa3b, v20
	v_mul_f32_e32 v20, 0xbfb8aa3b, v20
	v_exp_f32_e32 v21, v21
	v_exp_f32_e32 v20, v20
	s_waitcnt vmcnt(56)
	v_mul_f32_e32 v28, 0x3e3504f3, v28
	v_mul_f32_e32 v28, v28, v21
	v_mul_f32_e32 v29, v29, v20
	ds_write2st64_b32 v65, v28, v29 offset0:130 offset1:195
	v_add_f32_e32 v20, v11, v3
	v_mul_f32_e32 v21, 0x3fb8aa3b, v20
	v_mul_f32_e32 v20, 0xbfb8aa3b, v20
	v_exp_f32_e32 v21, v21
	v_exp_f32_e32 v20, v20
	s_waitcnt vmcnt(54)
	v_mul_f32_e32 v30, 0x3e3504f3, v30
	v_mul_f32_e32 v30, v30, v21
	v_mul_f32_e32 v31, v31, v20
	ds_write2st64_b32 v132, v30, v31 offset0:130 offset1:195
	v_add_f32_e32 v20, v9, v3
	v_mul_f32_e32 v21, 0x3fb8aa3b, v20
	v_mul_f32_e32 v20, 0xbfb8aa3b, v20
	v_exp_f32_e32 v21, v21
	v_exp_f32_e32 v20, v20
	s_waitcnt vmcnt(52)
	v_mul_f32_e32 v32, 0x3e3504f3, v32
	v_mul_f32_e32 v32, v32, v21
	v_mul_f32_e32 v33, v33, v20
	ds_write2st64_b32 v133, v32, v33 offset0:130 offset1:195
	v_add_f32_e32 v20, v7, v3
	v_mul_f32_e32 v21, 0x3fb8aa3b, v20
	v_mul_f32_e32 v20, 0xbfb8aa3b, v20
	v_exp_f32_e32 v21, v21
	v_exp_f32_e32 v20, v20
	s_waitcnt vmcnt(50)
	v_mul_f32_e32 v184, 0x3e3504f3, v184
	v_mul_f32_e32 v184, v184, v21
	v_mul_f32_e32 v185, v185, v20
	ds_write2st64_b32 v134, v184, v185 offset0:130 offset1:195
	v_add_f32_e32 v20, v5, v3
	v_mul_f32_e32 v21, 0x3fb8aa3b, v20
	v_mul_f32_e32 v20, 0xbfb8aa3b, v20
	v_exp_f32_e32 v21, v21
	v_exp_f32_e32 v20, v20
	s_waitcnt vmcnt(48)
	v_mul_f32_e32 v186, 0x3e3504f3, v186
	v_mul_f32_e32 v186, v186, v21
	v_mul_f32_e32 v187, v187, v20
	ds_write2st64_b32 v135, v186, v187 offset0:130 offset1:195
	v_mov_b32_e32 v2, 0
	v_mov_b32_e32 v3, 0
	v_mov_b32_e32 v4, 0
	v_mov_b32_e32 v5, 0
	v_mov_b32_e32 v6, 0
	v_mov_b32_e32 v7, 0
	v_mov_b32_e32 v8, 0
	v_mov_b32_e32 v9, 0
	v_mov_b32_e32 v10, 0
	v_mov_b32_e32 v11, 0
	v_mov_b32_e32 v12, 0
	v_mov_b32_e32 v13, 0
	v_mov_b32_e32 v14, 0
	v_mov_b32_e32 v15, 0
	v_mov_b32_e32 v16, 0
	v_mov_b32_e32 v17, 0
	s_waitcnt lgkmcnt(0)
	s_barrier
	s_and_saveexec_b64 vcc, s[50:51]
	s_cbranch_execz .LBB0_102
	v_mov_b32_e32 v2, 0
	s_mov_b32 s0, 0
	v_mov_b32_e32 v3, v2
	v_mov_b32_e32 v4, v2
	v_mov_b32_e32 v5, v2
	v_mov_b32_e32 v6, v2
	v_mov_b32_e32 v7, v2
	v_mov_b32_e32 v8, v2
	v_mov_b32_e32 v9, v2
	v_mov_b32_e32 v10, v2
	v_mov_b32_e32 v11, v2
	v_mov_b32_e32 v12, v2
	v_mov_b32_e32 v13, v2
	v_mov_b32_e32 v14, v2
	v_mov_b32_e32 v15, v2
	v_mov_b32_e32 v16, v2
	v_mov_b32_e32 v17, v2

	.amdhsa_kernel _Z4mega6Paramsii
		.amdhsa_group_segment_fixed_size 0
		.amdhsa_private_segment_fixed_size 0
		.amdhsa_kernarg_size 472
		.amdhsa_user_sgpr_count 2
		.amdhsa_user_sgpr_dispatch_ptr 0
		.amdhsa_user_sgpr_queue_ptr 0
		.amdhsa_user_sgpr_kernarg_segment_ptr 1
		.amdhsa_user_sgpr_dispatch_id 0
		.amdhsa_user_sgpr_kernarg_preload_length 0
		.amdhsa_user_sgpr_kernarg_preload_offset 0
		.amdhsa_user_sgpr_private_segment_size 0
		.amdhsa_uses_dynamic_stack 0
		.amdhsa_enable_private_segment 0
		.amdhsa_system_sgpr_workgroup_id_x 1
		.amdhsa_system_sgpr_workgroup_id_y 0
		.amdhsa_system_sgpr_workgroup_id_z 0
		.amdhsa_system_sgpr_workgroup_info 0
		.amdhsa_system_vgpr_workitem_id 0
		.amdhsa_next_free_vgpr 256
		.amdhsa_next_free_sgpr 102
		.amdhsa_accum_offset 256
		.amdhsa_reserve_vcc 1
		.amdhsa_float_round_mode_32 0
		.amdhsa_float_round_mode_16_64 0
		.amdhsa_float_denorm_mode_32 3
		.amdhsa_float_denorm_mode_16_64 3
		.amdhsa_dx10_clamp 1
		.amdhsa_ieee_mode 1
		.amdhsa_fp16_overflow 0
		.amdhsa_tg_split 0
		.amdhsa_exception_fp_ieee_invalid_op 0
		.amdhsa_exception_fp_denorm_src 0
		.amdhsa_exception_fp_ieee_div_zero 0
		.amdhsa_exception_fp_ieee_overflow 0
		.amdhsa_exception_fp_ieee_underflow 0
		.amdhsa_exception_fp_ieee_inexact 0
		.amdhsa_exception_int_div_zero 0
	.end_amdhsa_kernel

amdhsa.kernels:
  - .agpr_count:     0
    .args:
      - .offset:         0
        .size:           208
        .value_kind:     by_value
      - .offset:         208
        .size:           4
        .value_kind:     by_value
      - .offset:         212
        .size:           4
        .value_kind:     by_value
      - .offset:         216
        .size:           4
        .value_kind:     hidden_block_count_x
      - .offset:         220
        .size:           4
        .value_kind:     hidden_block_count_y
      - .offset:         224
        .size:           4
        .value_kind:     hidden_block_count_z
      - .offset:         228
        .size:           2
        .value_kind:     hidden_group_size_x
      - .offset:         230
        .size:           2
        .value_kind:     hidden_group_size_y
      - .offset:         232
        .size:           2
        .value_kind:     hidden_group_size_z
      - .offset:         234
        .size:           2
        .value_kind:     hidden_remainder_x
      - .offset:         236
        .size:           2
        .value_kind:     hidden_remainder_y
      - .offset:         238
        .size:           2
        .value_kind:     hidden_remainder_z
      - .offset:         256
        .size:           8
        .value_kind:     hidden_global_offset_x
      - .offset:         264
        .size:           8
        .value_kind:     hidden_global_offset_y
      - .offset:         272
        .size:           8
        .value_kind:     hidden_global_offset_z
      - .offset:         280
        .size:           2
        .value_kind:     hidden_grid_dims
      - .offset:         336
        .size:           4
        .value_kind:     hidden_dynamic_lds_size
    .group_segment_fixed_size: 0
    .kernarg_segment_align: 8
    .kernarg_segment_size: 472
    .language:       OpenCL C
    .language_version:
      - 2
      - 0
    .max_flat_workgroup_size: 256
    .name:           _Z4mega6Paramsii
    .private_segment_fixed_size: 0
    .sgpr_count:     108
    .sgpr_spill_count: 237
    .symbol:         _Z4mega6Paramsii.kd
    .uniform_work_group_size: 1
    .uses_dynamic_stack: false
    .vgpr_count:     256
    .vgpr_spill_count: 0
    .wavefront_size: 64
